# grid barrier: every WG polls the top arrival counter directly; agent acquire (buffer_inv sc1) moved before the arrival so it overlaps the wait (no cached loads between it and release)
# speedup vs baseline: 1.1569x; 1.0378x over previous
.LBB0_1457:
	buffer_inv sc1
	s_waitcnt vmcnt(0)
	s_mov_b64 s[4:5], exec
	v_mbcnt_lo_u32_b32 v1, s4, 0
	v_mbcnt_hi_u32_b32 v1, s5, v1
	v_cmp_eq_u32_e32 vcc, 0, v1
	s_and_saveexec_b64 s[2:3], vcc
	s_cbranch_execz .LBB0_1459
	s_bcnt1_i32_b64 s4, s[4:5]
	v_mov_b32_e32 v3, s4
	v_readlane_b32 s4, v254, 54
	v_readlane_b32 s5, v254, 55
	s_nop 4
	global_atomic_add v3, v177, v3, s[4:5] sc0
.LBB0_1459:
	s_or_b64 exec, exec, s[2:3]
	v_cvt_f32_u32_e32 v4, v2
	s_waitcnt vmcnt(0)
	v_readfirstlane_b32 s2, v3
	v_sub_u32_e32 v3, 0, v2
	v_rcp_iflag_f32_e32 v4, v4
	v_add_u32_e32 v5, s2, v1
	v_mul_f32_e32 v4, 0x4f7ffffe, v4
	v_cvt_u32_f32_e32 v4, v4
	v_mul_lo_u32 v1, v3, v4
	v_mul_hi_u32 v1, v4, v1
	v_add_u32_e32 v1, v4, v1
	v_mul_hi_u32 v1, v5, v1
	v_mul_lo_u32 v3, v1, v2
	v_sub_u32_e32 v3, v5, v3
	v_add_u32_e32 v4, 1, v1
	v_cmp_ge_u32_e32 vcc, v3, v2
	s_nop 1
	v_cndmask_b32_e32 v1, v1, v4, vcc
	v_sub_u32_e32 v4, v3, v2
	v_cndmask_b32_e32 v3, v3, v4, vcc
	v_add_u32_e32 v4, 1, v1
	v_cmp_ge_u32_e32 vcc, v3, v2
	v_add_u32_e32 v3, 1, v5
	s_nop 0
	v_cndmask_b32_e32 v1, v1, v4, vcc
	v_mul_lo_u32 v4, v2, v1
	v_add_u32_e32 v2, v4, v2
	v_cmp_ne_u32_e32 vcc, v3, v2
	s_waitcnt lgkmcnt(0)
	v_add_u32_e32 v1, 1, v1
	v_mul_lo_u32 v1, v1, v0
	v_readlane_b32 s4, v254, 58
	v_readlane_b32 s5, v254, 59
	s_mov_b32 s16, 0
	s_nop 3
	s_cbranch_vccnz .Lxb_spin
	buffer_wbl2 sc1
	s_waitcnt vmcnt(0) lgkmcnt(0)
	v_mov_b32_e32 v2, 1
	global_atomic_add v177, v2, s[4:5]
.Lxb_spin:
	global_load_dword v0, v177, s[4:5] sc1
	s_waitcnt vmcnt(0)
	v_sub_u32_e32 v0, v0, v1
	v_cmp_le_i32_e32 vcc, 0, v0
	s_cbranch_vccnz .Lxb_done
	s_sleep 1
	s_add_i32 s16, s16, 1
	s_and_b32 s12, s16, 0xff
	s_cmp_lg_u32 s12, 0
	s_cbranch_scc1 .Lxb_spin
	global_load_dword v0, v177, s[82:83] sc1
	s_waitcnt vmcnt(0)
	v_cmp_ne_u32_e32 vcc, 0, v0
	s_cbranch_vccnz .Lxb_done
	s_cmp_lt_u32 s16, 0x400001
	s_cbranch_scc1 .Lxb_spin
	v_mov_b32_e32 v0, 1
	global_atomic_add v177, v0, s[82:83]
.Lxb_done:
	s_waitcnt vmcnt(0)
	s_getpc_b64 s[98:99]
